# P1 weight-conversion: batch the 16 serialized gain loads per item into one wait (3 sites)
# speedup vs baseline: 1.0060x; 1.0060x over previous
; __device__ __forceinline__ void tr_item(const float* W, int K, int N, bf16_t* WT, const float* gain, int perm, LAS float* scr, int item, int lane) {
;     const int nblk = N / 64, kb = item / nblk, nb = item % nblk, k0 = 64 * kb, n0 = 64 * nb, lr = lane >> 4, c4 = lane & 15;
;     f32x4 v[16];
; #pragma unroll
;     for (int i = 0; i < 16; ++i) v[i] = *(const f32x4*)(W + (size_t)(k0 + lr + 4 * i) * N + n0 + 4 * c4);
;     if (gain) {
; #pragma unroll
;         for (int i = 0; i < 16; ++i) v[i] = v[i] * gain[k0 + lr + 4 * i];
;     }
.LBB0_613:
	s_andn2_b64 vcc, exec, s[6:7]
	s_cbranch_vccnz .LBB0_617
	s_and_b64 s[6:7], s[0:1], exec
	v_readlane_b32 s16, v254, 11
	s_cselect_b32 s6, 0x2800000, 0
	v_readlane_b32 s30, v254, 25
	v_readlane_b32 s31, v254, 26
	s_add_u32 s6, s30, s6
	v_readlane_b32 s17, v254, 12
	s_addc_u32 s7, s31, 0
	s_add_i32 s9, s8, 0xbe00
	s_and_b32 s17, s9, 0xffff
	v_readlane_b32 s18, v254, 13
	s_mul_i32 s17, s17, 0xcccd
	s_lshr_b32 s18, s17, 16
	s_lshr_b32 s17, s17, 22
	v_readlane_b32 s19, v254, 14
	s_mulk_i32 s17, 0x50
	s_sub_i32 s19, s9, s17
	s_and_b32 s9, s18, 0xffc0
	s_lshl_b32 s18, s19, 8
	s_lshl_b32 s17, s19, 6
	s_and_b32 s18, s18, 0x3ff00
	s_add_u32 s6, s6, s18
	v_or_b32_e32 v68, s9, v70
	s_addc_u32 s7, s7, 0
	v_lshlrev_b32_e32 v128, 2, v64
	v_lshl_add_u64 v[0:1], s[6:7], 0, v[128:129]
	s_movk_i32 s16, 0x5000
	v_or_b32_e32 v4, 4, v68
	v_mad_u64_u32 v[2:3], s[6:7], v68, s16, v[0:1]
	v_mad_u64_u32 v[4:5], s[6:7], v4, s16, v[0:1]
	global_load_dwordx4 v[60:63], v[2:3], off
	global_load_dwordx4 v[48:51], v[4:5], off
	v_or_b32_e32 v2, 8, v68
	v_or_b32_e32 v4, 12, v68
	v_mad_u64_u32 v[2:3], s[6:7], v2, s16, v[0:1]
	v_mad_u64_u32 v[4:5], s[6:7], v4, s16, v[0:1]
	global_load_dwordx4 v[56:59], v[2:3], off
	global_load_dwordx4 v[40:43], v[4:5], off
	v_or_b32_e32 v2, 16, v68
	v_or_b32_e32 v4, 20, v68
	v_mad_u64_u32 v[2:3], s[6:7], v2, s16, v[0:1]
	v_mad_u64_u32 v[4:5], s[6:7], v4, s16, v[0:1]
	global_load_dwordx4 v[52:55], v[2:3], off
	global_load_dwordx4 v[32:35], v[4:5], off
	v_or_b32_e32 v2, 24, v68
	v_or_b32_e32 v4, 28, v68
	v_mad_u64_u32 v[2:3], s[6:7], v2, s16, v[0:1]
	v_mad_u64_u32 v[4:5], s[6:7], v4, s16, v[0:1]
	global_load_dwordx4 v[44:47], v[2:3], off
	global_load_dwordx4 v[24:27], v[4:5], off
	v_or_b32_e32 v2, 32, v68
	v_or_b32_e32 v4, 36, v68
	v_mad_u64_u32 v[2:3], s[6:7], v2, s16, v[0:1]
	v_mad_u64_u32 v[4:5], s[6:7], v4, s16, v[0:1]
	global_load_dwordx4 v[36:39], v[2:3], off
	global_load_dwordx4 v[12:15], v[4:5], off
	v_or_b32_e32 v2, 40, v68
	v_or_b32_e32 v4, 44, v68
	v_mad_u64_u32 v[2:3], s[6:7], v2, s16, v[0:1]
	v_mad_u64_u32 v[4:5], s[6:7], v4, s16, v[0:1]
	global_load_dwordx4 v[28:31], v[2:3], off
	global_load_dwordx4 v[8:11], v[4:5], off
	v_or_b32_e32 v2, 48, v68
	v_or_b32_e32 v4, 52, v68
	v_mad_u64_u32 v[2:3], s[6:7], v2, s16, v[0:1]
	v_mad_u64_u32 v[4:5], s[6:7], v4, s16, v[0:1]
	global_load_dwordx4 v[20:23], v[2:3], off
	s_nop 0
	global_load_dwordx4 v[4:7], v[4:5], off
	v_or_b32_e32 v2, 56, v68
	v_or_b32_e32 v16, 60, v68
	v_mad_u64_u32 v[2:3], s[6:7], v2, s16, v[0:1]
	v_mad_u64_u32 v[0:1], s[6:7], v16, s16, v[0:1]
	global_load_dwordx4 v[16:19], v[2:3], off
	s_nop 0
	global_load_dwordx4 v[0:3], v[0:1], off
	v_readlane_b32 s6, v254, 2
	v_readlane_b32 s7, v254, 3
	v_readlane_b32 s28, v254, 23
	v_readlane_b32 s29, v254, 24
	s_andn2_b64 vcc, exec, s[6:7]
	v_readlane_b32 s20, v254, 15
	v_readlane_b32 s21, v254, 16
	v_readlane_b32 s22, v254, 17
	v_readlane_b32 s23, v254, 18
	v_readlane_b32 s24, v254, 19
	v_readlane_b32 s25, v254, 20
	v_readlane_b32 s26, v254, 21
	v_readlane_b32 s27, v254, 22
	s_cbranch_vccnz .LBB0_616
	s_and_b64 s[6:7], s[0:1], exec
	s_cselect_b32 s6, 0x2000, 0
	s_add_u32 s6, s28, s6
	s_addc_u32 s7, s29, 0
	v_lshlrev_b32_e32 v69, 2, v68
	global_load_dword v84, v69, s[6:7]
	global_load_dword v86, v69, s[6:7] offset:16
	global_load_dword v88, v69, s[6:7] offset:32
	global_load_dword v90, v69, s[6:7] offset:48
	global_load_dword v92, v69, s[6:7] offset:64
	global_load_dword v94, v69, s[6:7] offset:80
	global_load_dword v96, v69, s[6:7] offset:96
	global_load_dword v98, v69, s[6:7] offset:112
	global_load_dword v100, v69, s[6:7] offset:128
	global_load_dword v102, v69, s[6:7] offset:144
	global_load_dword v104, v69, s[6:7] offset:160
	global_load_dword v106, v69, s[6:7] offset:176
	global_load_dword v108, v69, s[6:7] offset:192
	global_load_dword v110, v69, s[6:7] offset:208
	global_load_dword v112, v69, s[6:7] offset:224
	global_load_dword v114, v69, s[6:7] offset:240
	s_waitcnt vmcnt(0)
	v_pk_mul_f32 v[62:63], v[62:63], v[84:85] op_sel_hi:[1,0]
	v_pk_mul_f32 v[60:61], v[60:61], v[84:85] op_sel_hi:[1,0]
	v_pk_mul_f32 v[50:51], v[50:51], v[86:87] op_sel_hi:[1,0]
	v_pk_mul_f32 v[48:49], v[48:49], v[86:87] op_sel_hi:[1,0]
	v_pk_mul_f32 v[58:59], v[58:59], v[88:89] op_sel_hi:[1,0]
	v_pk_mul_f32 v[56:57], v[56:57], v[88:89] op_sel_hi:[1,0]
	v_pk_mul_f32 v[42:43], v[42:43], v[90:91] op_sel_hi:[1,0]
	v_pk_mul_f32 v[40:41], v[40:41], v[90:91] op_sel_hi:[1,0]
	v_pk_mul_f32 v[54:55], v[54:55], v[92:93] op_sel_hi:[1,0]
	v_pk_mul_f32 v[52:53], v[52:53], v[92:93] op_sel_hi:[1,0]
	v_pk_mul_f32 v[34:35], v[34:35], v[94:95] op_sel_hi:[1,0]
	v_pk_mul_f32 v[32:33], v[32:33], v[94:95] op_sel_hi:[1,0]
	v_pk_mul_f32 v[46:47], v[46:47], v[96:97] op_sel_hi:[1,0]
	v_pk_mul_f32 v[44:45], v[44:45], v[96:97] op_sel_hi:[1,0]
	v_pk_mul_f32 v[26:27], v[26:27], v[98:99] op_sel_hi:[1,0]
	v_pk_mul_f32 v[24:25], v[24:25], v[98:99] op_sel_hi:[1,0]
	v_pk_mul_f32 v[38:39], v[38:39], v[100:101] op_sel_hi:[1,0]
	v_pk_mul_f32 v[36:37], v[36:37], v[100:101] op_sel_hi:[1,0]
	v_pk_mul_f32 v[14:15], v[14:15], v[102:103] op_sel_hi:[1,0]
	v_pk_mul_f32 v[12:13], v[12:13], v[102:103] op_sel_hi:[1,0]
	v_pk_mul_f32 v[30:31], v[30:31], v[104:105] op_sel_hi:[1,0]
	v_pk_mul_f32 v[28:29], v[28:29], v[104:105] op_sel_hi:[1,0]
	v_pk_mul_f32 v[10:11], v[10:11], v[106:107] op_sel_hi:[1,0]
	v_pk_mul_f32 v[8:9], v[8:9], v[106:107] op_sel_hi:[1,0]
	v_pk_mul_f32 v[22:23], v[22:23], v[108:109] op_sel_hi:[1,0]
	v_pk_mul_f32 v[20:21], v[20:21], v[108:109] op_sel_hi:[1,0]
	v_pk_mul_f32 v[6:7], v[6:7], v[110:111] op_sel_hi:[1,0]
	v_pk_mul_f32 v[4:5], v[4:5], v[110:111] op_sel_hi:[1,0]
	v_pk_mul_f32 v[18:19], v[18:19], v[112:113] op_sel_hi:[1,0]
	v_pk_mul_f32 v[16:17], v[16:17], v[112:113] op_sel_hi:[1,0]
	v_pk_mul_f32 v[2:3], v[2:3], v[114:115] op_sel_hi:[1,0]
	v_pk_mul_f32 v[0:1], v[0:1], v[114:115] op_sel_hi:[1,0]

; __device__ __forceinline__ void tr_item(const float* W, int K, int N, bf16_t* WT, const float* gain, int perm, LAS float* scr, int item, int lane) {
;     const int nblk = N / 64, kb = item / nblk, nb = item % nblk, k0 = 64 * kb, n0 = 64 * nb, lr = lane >> 4, c4 = lane & 15;
;     f32x4 v[16];
; #pragma unroll
;     for (int i = 0; i < 16; ++i) v[i] = *(const f32x4*)(W + (size_t)(k0 + lr + 4 * i) * N + n0 + 4 * c4);
;     if (gain) {
; #pragma unroll
;         for (int i = 0; i < 16; ++i) v[i] = v[i] * gain[k0 + lr + 4 * i];
;     }
.LBB0_624:
	s_andn2_b64 vcc, exec, s[6:7]
	s_cbranch_vccnz .LBB0_628
	s_and_b64 s[6:7], s[0:1], exec
	s_cselect_b32 s6, 0x5800000, 0
	s_add_u32 s6, s54, s6
	s_addc_u32 s7, s55, 0
	s_add_i32 s9, s8, 0xea00
	s_and_b32 s17, s9, 0xffff
	s_mul_i32 s17, s17, 0xba2f
	s_lshr_b32 s17, s17, 23
	s_mul_i32 s18, s17, 0xb0
	s_sub_i32 s9, s9, s18
	s_lshl_b32 s19, s9, 8
	s_lshl_b32 s17, s17, 6
	s_lshl_b32 s18, s9, 6
	s_and_b32 s19, s19, 0x3ff00
	s_add_u32 s6, s6, s19
	v_or_b32_e32 v68, s17, v70
	s_addc_u32 s7, s7, 0
	v_lshlrev_b32_e32 v128, 2, v64
	v_lshl_add_u64 v[0:1], s[6:7], 0, v[128:129]
	v_or_b32_e32 v4, 4, v68
	v_mad_u64_u32 v[2:3], s[6:7], v68, s63, v[0:1]
	v_mad_u64_u32 v[4:5], s[6:7], v4, s63, v[0:1]
	global_load_dwordx4 v[60:63], v[2:3], off
	global_load_dwordx4 v[48:51], v[4:5], off
	v_or_b32_e32 v2, 8, v68
	v_or_b32_e32 v4, 12, v68
	v_mad_u64_u32 v[2:3], s[6:7], v2, s63, v[0:1]
	v_mad_u64_u32 v[4:5], s[6:7], v4, s63, v[0:1]
	global_load_dwordx4 v[56:59], v[2:3], off
	global_load_dwordx4 v[40:43], v[4:5], off
	v_or_b32_e32 v2, 16, v68
	v_or_b32_e32 v4, 20, v68
	v_mad_u64_u32 v[2:3], s[6:7], v2, s63, v[0:1]
	v_mad_u64_u32 v[4:5], s[6:7], v4, s63, v[0:1]
	global_load_dwordx4 v[52:55], v[2:3], off
	global_load_dwordx4 v[32:35], v[4:5], off
	v_or_b32_e32 v2, 24, v68
	v_or_b32_e32 v4, 28, v68
	v_mad_u64_u32 v[2:3], s[6:7], v2, s63, v[0:1]
	v_mad_u64_u32 v[4:5], s[6:7], v4, s63, v[0:1]
	global_load_dwordx4 v[44:47], v[2:3], off
	global_load_dwordx4 v[24:27], v[4:5], off
	v_or_b32_e32 v2, 32, v68
	v_or_b32_e32 v4, 36, v68
	v_mad_u64_u32 v[2:3], s[6:7], v2, s63, v[0:1]
	v_mad_u64_u32 v[4:5], s[6:7], v4, s63, v[0:1]
	global_load_dwordx4 v[36:39], v[2:3], off
	global_load_dwordx4 v[16:19], v[4:5], off
	v_or_b32_e32 v2, 40, v68
	v_or_b32_e32 v4, 44, v68
	v_mad_u64_u32 v[2:3], s[6:7], v2, s63, v[0:1]
	v_mad_u64_u32 v[4:5], s[6:7], v4, s63, v[0:1]
	global_load_dwordx4 v[28:31], v[2:3], off
	global_load_dwordx4 v[8:11], v[4:5], off
	v_or_b32_e32 v2, 48, v68
	v_or_b32_e32 v4, 52, v68
	v_mad_u64_u32 v[2:3], s[6:7], v2, s63, v[0:1]
	v_mad_u64_u32 v[4:5], s[6:7], v4, s63, v[0:1]
	global_load_dwordx4 v[20:23], v[2:3], off
	s_nop 0
	global_load_dwordx4 v[4:7], v[4:5], off
	v_or_b32_e32 v2, 56, v68
	v_or_b32_e32 v12, 60, v68
	v_mad_u64_u32 v[2:3], s[6:7], v2, s63, v[0:1]
	v_mad_u64_u32 v[0:1], s[6:7], v12, s63, v[0:1]
	global_load_dwordx4 v[12:15], v[2:3], off
	s_nop 0
	global_load_dwordx4 v[0:3], v[0:1], off
	v_readlane_b32 s6, v254, 4
	v_readlane_b32 s7, v254, 5
	s_andn2_b64 vcc, exec, s[6:7]
	s_cbranch_vccnz .LBB0_627
	s_and_b64 s[6:7], s[0:1], exec
	s_cselect_b32 s6, 0x2000, 0
	s_add_u32 s6, s52, s6
	s_addc_u32 s7, s53, 0
	v_lshlrev_b32_e32 v69, 2, v68
	global_load_dword v84, v69, s[6:7]
	global_load_dword v86, v69, s[6:7] offset:16
	global_load_dword v88, v69, s[6:7] offset:32
	global_load_dword v90, v69, s[6:7] offset:48
	global_load_dword v92, v69, s[6:7] offset:64
	global_load_dword v94, v69, s[6:7] offset:80
	global_load_dword v96, v69, s[6:7] offset:96
	global_load_dword v98, v69, s[6:7] offset:112
	global_load_dword v100, v69, s[6:7] offset:128
	global_load_dword v102, v69, s[6:7] offset:144
	global_load_dword v104, v69, s[6:7] offset:160
	global_load_dword v106, v69, s[6:7] offset:176
	global_load_dword v108, v69, s[6:7] offset:192
	global_load_dword v110, v69, s[6:7] offset:208
	global_load_dword v112, v69, s[6:7] offset:224
	global_load_dword v114, v69, s[6:7] offset:240
	s_waitcnt vmcnt(0)
	v_pk_mul_f32 v[62:63], v[62:63], v[84:85] op_sel_hi:[1,0]
	v_pk_mul_f32 v[60:61], v[60:61], v[84:85] op_sel_hi:[1,0]
	v_pk_mul_f32 v[50:51], v[50:51], v[86:87] op_sel_hi:[1,0]
	v_pk_mul_f32 v[48:49], v[48:49], v[86:87] op_sel_hi:[1,0]
	v_pk_mul_f32 v[58:59], v[58:59], v[88:89] op_sel_hi:[1,0]
	v_pk_mul_f32 v[56:57], v[56:57], v[88:89] op_sel_hi:[1,0]
	v_pk_mul_f32 v[42:43], v[42:43], v[90:91] op_sel_hi:[1,0]
	v_pk_mul_f32 v[40:41], v[40:41], v[90:91] op_sel_hi:[1,0]
	v_pk_mul_f32 v[54:55], v[54:55], v[92:93] op_sel_hi:[1,0]
	v_pk_mul_f32 v[52:53], v[52:53], v[92:93] op_sel_hi:[1,0]
	v_pk_mul_f32 v[34:35], v[34:35], v[94:95] op_sel_hi:[1,0]
	v_pk_mul_f32 v[32:33], v[32:33], v[94:95] op_sel_hi:[1,0]
	v_pk_mul_f32 v[46:47], v[46:47], v[96:97] op_sel_hi:[1,0]
	v_pk_mul_f32 v[44:45], v[44:45], v[96:97] op_sel_hi:[1,0]
	v_pk_mul_f32 v[26:27], v[26:27], v[98:99] op_sel_hi:[1,0]
	v_pk_mul_f32 v[24:25], v[24:25], v[98:99] op_sel_hi:[1,0]
	v_pk_mul_f32 v[38:39], v[38:39], v[100:101] op_sel_hi:[1,0]
	v_pk_mul_f32 v[36:37], v[36:37], v[100:101] op_sel_hi:[1,0]
	v_pk_mul_f32 v[18:19], v[18:19], v[102:103] op_sel_hi:[1,0]
	v_pk_mul_f32 v[16:17], v[16:17], v[102:103] op_sel_hi:[1,0]
	v_pk_mul_f32 v[30:31], v[30:31], v[104:105] op_sel_hi:[1,0]
	v_pk_mul_f32 v[28:29], v[28:29], v[104:105] op_sel_hi:[1,0]
	v_pk_mul_f32 v[10:11], v[10:11], v[106:107] op_sel_hi:[1,0]
	v_pk_mul_f32 v[8:9], v[8:9], v[106:107] op_sel_hi:[1,0]
	v_pk_mul_f32 v[22:23], v[22:23], v[108:109] op_sel_hi:[1,0]
	v_pk_mul_f32 v[20:21], v[20:21], v[108:109] op_sel_hi:[1,0]
	v_pk_mul_f32 v[6:7], v[6:7], v[110:111] op_sel_hi:[1,0]
	v_pk_mul_f32 v[4:5], v[4:5], v[110:111] op_sel_hi:[1,0]
	v_pk_mul_f32 v[14:15], v[14:15], v[112:113] op_sel_hi:[1,0]
	v_pk_mul_f32 v[12:13], v[12:13], v[112:113] op_sel_hi:[1,0]
	v_pk_mul_f32 v[2:3], v[2:3], v[114:115] op_sel_hi:[1,0]
	v_pk_mul_f32 v[0:1], v[0:1], v[114:115] op_sel_hi:[1,0]

; __device__ __forceinline__ void tr_item(const float* W, int K, int N, bf16_t* WT, const float* gain, int perm, LAS float* scr, int item, int lane) {
;     const int nblk = N / 64, kb = item / nblk, nb = item % nblk, k0 = 64 * kb, n0 = 64 * nb, lr = lane >> 4, c4 = lane & 15;
;     f32x4 v[16];
; #pragma unroll
;     for (int i = 0; i < 16; ++i) v[i] = *(const f32x4*)(W + (size_t)(k0 + lr + 4 * i) * N + n0 + 4 * c4);
;     if (gain) {
; #pragma unroll
;         for (int i = 0; i < 16; ++i) v[i] = v[i] * gain[k0 + lr + 4 * i];
;     }
.LBB0_630:
	s_and_b64 s[6:7], s[0:1], exec
	v_readlane_b32 s16, v254, 11
	s_cselect_b32 s6, 0x5800000, 0
	v_readlane_b32 s24, v254, 19
	v_readlane_b32 s17, v254, 12
	v_readlane_b32 s25, v254, 20
	s_add_u32 s9, s24, s6
	s_mul_hi_i32 s6, s8, 0x2e8ba2e9
	s_addc_u32 s17, s25, 0
	s_lshr_b32 s7, s6, 31
	s_ashr_i32 s6, s6, 5
	s_add_i32 s6, s6, s7
	s_mul_i32 s7, s6, 0xb0
	s_sub_i32 s7, s8, s7
	s_lshl_b32 s8, s6, 6
	s_lshl_b32 s6, s7, 6
	v_readlane_b32 s18, v254, 13
	v_readlane_b32 s19, v254, 14
	s_ashr_i32 s7, s6, 31
	s_lshl_b64 s[18:19], s[6:7], 2
	s_add_u32 s18, s9, s18
	v_or_b32_e32 v68, s8, v70
	s_addc_u32 s19, s17, s19
	v_lshlrev_b32_e32 v128, 2, v64
	v_lshl_add_u64 v[0:1], s[18:19], 0, v[128:129]
	v_or_b32_e32 v4, 4, v68
	v_mad_i64_i32 v[2:3], s[18:19], v68, s63, v[0:1]
	v_mad_i64_i32 v[4:5], s[18:19], v4, s63, v[0:1]
	global_load_dwordx4 v[60:63], v[2:3], off
	global_load_dwordx4 v[48:51], v[4:5], off
	v_or_b32_e32 v2, 8, v68
	v_or_b32_e32 v4, 12, v68
	v_mad_i64_i32 v[2:3], s[18:19], v2, s63, v[0:1]
	v_mad_i64_i32 v[4:5], s[18:19], v4, s63, v[0:1]
	global_load_dwordx4 v[56:59], v[2:3], off
	global_load_dwordx4 v[40:43], v[4:5], off
	v_or_b32_e32 v2, 16, v68
	v_or_b32_e32 v4, 20, v68
	v_mad_i64_i32 v[2:3], s[18:19], v2, s63, v[0:1]
	v_mad_i64_i32 v[4:5], s[18:19], v4, s63, v[0:1]
	global_load_dwordx4 v[52:55], v[2:3], off
	global_load_dwordx4 v[32:35], v[4:5], off
	v_or_b32_e32 v2, 24, v68
	v_or_b32_e32 v4, 28, v68
	v_mad_i64_i32 v[2:3], s[18:19], v2, s63, v[0:1]
	v_mad_i64_i32 v[4:5], s[18:19], v4, s63, v[0:1]
	global_load_dwordx4 v[44:47], v[2:3], off
	global_load_dwordx4 v[24:27], v[4:5], off
	v_or_b32_e32 v2, 32, v68
	v_or_b32_e32 v4, 36, v68
	v_mad_i64_i32 v[2:3], s[18:19], v2, s63, v[0:1]
	v_mad_i64_i32 v[4:5], s[18:19], v4, s63, v[0:1]
	global_load_dwordx4 v[36:39], v[2:3], off
	global_load_dwordx4 v[16:19], v[4:5], off
	v_or_b32_e32 v2, 40, v68
	v_or_b32_e32 v4, 44, v68
	v_mad_i64_i32 v[2:3], s[18:19], v2, s63, v[0:1]
	v_mad_i64_i32 v[4:5], s[18:19], v4, s63, v[0:1]
	global_load_dwordx4 v[28:31], v[2:3], off
	global_load_dwordx4 v[8:11], v[4:5], off
	v_or_b32_e32 v2, 48, v68
	v_or_b32_e32 v4, 52, v68
	v_mad_i64_i32 v[2:3], s[18:19], v2, s63, v[0:1]
	v_mad_i64_i32 v[4:5], s[18:19], v4, s63, v[0:1]
	global_load_dwordx4 v[20:23], v[2:3], off
	s_nop 0
	global_load_dwordx4 v[4:7], v[4:5], off
	v_or_b32_e32 v2, 56, v68
	v_or_b32_e32 v12, 60, v68
	v_mad_i64_i32 v[2:3], s[18:19], v2, s63, v[0:1]
	v_mad_i64_i32 v[0:1], s[18:19], v12, s63, v[0:1]
	global_load_dwordx4 v[12:15], v[2:3], off
	s_nop 0
	global_load_dwordx4 v[0:3], v[0:1], off
	v_readlane_b32 s16, v254, 6
	v_readlane_b32 s17, v254, 7
	v_readlane_b32 s22, v254, 17
	v_readlane_b32 s23, v254, 18
	s_andn2_b64 vcc, exec, s[16:17]
	v_readlane_b32 s20, v254, 15
	v_readlane_b32 s21, v254, 16
	v_readlane_b32 s26, v254, 21
	v_readlane_b32 s27, v254, 22
	v_readlane_b32 s28, v254, 23
	v_readlane_b32 s29, v254, 24
	v_readlane_b32 s30, v254, 25
	v_readlane_b32 s31, v254, 26
	s_cbranch_vccnz .LBB0_605
	s_and_b64 s[0:1], s[0:1], exec
	s_cselect_b32 s0, 0x2000, 0
	s_add_u32 s0, s22, s0
	v_ashrrev_i32_e32 v69, 31, v68
	s_addc_u32 s1, s23, 0
	v_lshl_add_u64 v[68:69], v[68:69], 2, s[0:1]
	global_load_dword v84, v[68:69], off
	global_load_dword v86, v[68:69], off offset:16
	global_load_dword v88, v[68:69], off offset:32
	global_load_dword v90, v[68:69], off offset:48
	global_load_dword v92, v[68:69], off offset:64
	global_load_dword v94, v[68:69], off offset:80
	global_load_dword v96, v[68:69], off offset:96
	global_load_dword v98, v[68:69], off offset:112
	global_load_dword v100, v[68:69], off offset:128
	global_load_dword v102, v[68:69], off offset:144
	global_load_dword v104, v[68:69], off offset:160
	global_load_dword v106, v[68:69], off offset:176
	global_load_dword v108, v[68:69], off offset:192
	global_load_dword v110, v[68:69], off offset:208
	global_load_dword v112, v[68:69], off offset:224
	global_load_dword v114, v[68:69], off offset:240
	s_waitcnt vmcnt(0)
	v_pk_mul_f32 v[62:63], v[62:63], v[84:85] op_sel_hi:[1,0]
	v_pk_mul_f32 v[60:61], v[60:61], v[84:85] op_sel_hi:[1,0]
	v_pk_mul_f32 v[50:51], v[50:51], v[86:87] op_sel_hi:[1,0]
	v_pk_mul_f32 v[48:49], v[48:49], v[86:87] op_sel_hi:[1,0]
	v_pk_mul_f32 v[58:59], v[58:59], v[88:89] op_sel_hi:[1,0]
	v_pk_mul_f32 v[56:57], v[56:57], v[88:89] op_sel_hi:[1,0]
	v_pk_mul_f32 v[42:43], v[42:43], v[90:91] op_sel_hi:[1,0]
	v_pk_mul_f32 v[40:41], v[40:41], v[90:91] op_sel_hi:[1,0]
	v_pk_mul_f32 v[54:55], v[54:55], v[92:93] op_sel_hi:[1,0]
	v_pk_mul_f32 v[52:53], v[52:53], v[92:93] op_sel_hi:[1,0]
	v_pk_mul_f32 v[34:35], v[34:35], v[94:95] op_sel_hi:[1,0]
	v_pk_mul_f32 v[32:33], v[32:33], v[94:95] op_sel_hi:[1,0]
	v_pk_mul_f32 v[46:47], v[46:47], v[96:97] op_sel_hi:[1,0]
	v_pk_mul_f32 v[44:45], v[44:45], v[96:97] op_sel_hi:[1,0]
	v_pk_mul_f32 v[26:27], v[26:27], v[98:99] op_sel_hi:[1,0]
	v_pk_mul_f32 v[24:25], v[24:25], v[98:99] op_sel_hi:[1,0]
	v_pk_mul_f32 v[38:39], v[38:39], v[100:101] op_sel_hi:[1,0]
	v_pk_mul_f32 v[36:37], v[36:37], v[100:101] op_sel_hi:[1,0]
	v_pk_mul_f32 v[18:19], v[18:19], v[102:103] op_sel_hi:[1,0]
	v_pk_mul_f32 v[16:17], v[16:17], v[102:103] op_sel_hi:[1,0]
	v_pk_mul_f32 v[30:31], v[30:31], v[104:105] op_sel_hi:[1,0]
	v_pk_mul_f32 v[28:29], v[28:29], v[104:105] op_sel_hi:[1,0]
	v_pk_mul_f32 v[10:11], v[10:11], v[106:107] op_sel_hi:[1,0]
	v_pk_mul_f32 v[8:9], v[8:9], v[106:107] op_sel_hi:[1,0]
	v_pk_mul_f32 v[22:23], v[22:23], v[108:109] op_sel_hi:[1,0]
	v_pk_mul_f32 v[20:21], v[20:21], v[108:109] op_sel_hi:[1,0]
	v_pk_mul_f32 v[6:7], v[6:7], v[110:111] op_sel_hi:[1,0]
	v_pk_mul_f32 v[4:5], v[4:5], v[110:111] op_sel_hi:[1,0]
	v_pk_mul_f32 v[14:15], v[14:15], v[112:113] op_sel_hi:[1,0]
	v_pk_mul_f32 v[12:13], v[12:13], v[112:113] op_sel_hi:[1,0]
	v_pk_mul_f32 v[2:3], v[2:3], v[114:115] op_sel_hi:[1,0]
	v_pk_mul_f32 v[0:1], v[0:1], v[114:115] op_sel_hi:[1,0]
	s_branch .LBB0_605
